# one static s_setprio 1 for waves 0-3 at kernel entry, per-phase flips removed (timing only)
# baseline (speedup 1.0000x reference)
; #define LAS __attribute__((address_space(3)))
; __global__ void __launch_bounds__(512, 2) fwd(Params P) {
;     extern __shared__ __attribute__((aligned(16))) unsigned char shm[];
;     cg::grid_group grid = cg::this_grid();
;     const int lo = P.ph_lo, hi = P.ph_hi;
;     const int tid = threadIdx.x, wave = tid >> 6;
;     unsigned char* ws = P.ws;
;     volatile LAS unsigned* bst = (volatile LAS unsigned*)((LAS unsigned char*)shm + BARST_OFF);
;     if (tid == 0) { bst[0] = 0u; bst[1] = 0u; }
;     __syncthreads();
;     XcdBarrier xbar = xcd_barrier_post((unsigned*)(ws + O_BAR), bst);
_Z3fwd6Params:
	s_load_dword s93, s[0:1], 0x118
	s_load_dwordx4 s[12:15], s[0:1], 0x100
	s_load_dwordx2 s[96:97], s[0:1], 0x110
	s_add_u32 s4, s0, 0x110
	v_and_b32_e32 v214, 0x3ff, v0
	s_mov_b32 s94, s2
	s_addc_u32 s5, s1, 0
	v_readfirstlane_b32 s3, v214
	s_nop 3
	s_cmpk_ge_u32 s3, 0x100
	s_cbranch_scc1 .Lprio_done
	s_setprio 1
.Lprio_done:
	v_cmp_eq_u32_e64 s[88:89], 0, v214
	s_and_saveexec_b64 s[2:3], s[88:89]
	s_cbranch_execz .LBB0_2
	s_add_i32 s6, 0, 0x25e80
	v_mov_b32_e32 v1, 0
	v_mov_b32_e32 v2, s6
	s_add_i32 s6, 0, 0x25e84
	ds_write_b32 v2, v1
	v_mov_b32_e32 v2, s6
	ds_write_b32 v2, v1
